# GQA item prologue: first K/V tile global loads issued at item-start barrier into loop-temp VGPRs
# speedup vs baseline: 1.0087x; 1.0028x over previous
.LBB0_282:
	s_and_b32 s11, s22, 7
	s_mul_hi_i32 s9, s8, 0x1400
	s_mulk_i32 s8, 0x1400
	s_add_u32 s8, s16, s8
	s_addc_u32 s9, s17, s9
	s_lshl_b32 s13, s11, 8
	s_add_u32 s8, s8, s13
	s_addc_u32 s9, s9, 0
	v_lshl_add_u64 v[2:3], s[8:9], 0, v[180:181]
	v_lshl_add_u64 v[2:3], v[2:3], 0, v[0:1]
	s_barrier
	s_lshl_b32 s36, s11, 6
	s_and_b32 s36, s36, 0x100
	s_add_u32 s38, s20, s36
	s_addc_u32 s39, s21, 0
	s_add_u32 s36, s18, s36
	s_addc_u32 s37, s19, 0
	s_mov_b32 s100, s10
	s_ashr_i32 s101, s10, 31
	v_lshl_add_u64 v[238:239], s[100:101], 0, v[184:185]
	v_mov_b64_e32 v[240:241], s[36:37]
	v_mad_u64_u32 v[242:243], s[24:25], v238, s65, v[240:241]
	v_mad_i32_i24 v243, v239, s65, v243
	v_mov_b32_e32 v195, v1
	v_lshl_add_u64 v[246:247], v[242:243], 0, v[194:195]
	v_lshl_add_u64 v[242:243], v[186:187], 0, s[100:101]
	v_mad_u64_u32 v[240:241], s[24:25], v242, s65, v[240:241]
	v_mad_i32_i24 v241, v243, s65, v241
	v_lshl_add_u64 v[162:163], v[240:241], 0, v[194:195]
	v_mov_b64_e32 v[240:241], s[38:39]
	v_mad_u64_u32 v[244:245], s[24:25], v238, s65, v[240:241]
	v_mad_u64_u32 v[240:241], s[24:25], v242, s65, v[240:241]
	v_mad_i32_i24 v245, v239, s65, v245
	v_mad_i32_i24 v241, v243, s65, v241
	v_lshl_add_u64 v[238:239], v[244:245], 0, v[194:195]
	v_lshl_add_u64 v[242:243], v[240:241], 0, v[194:195]
	global_load_dwordx4 v[238:241], v[238:239], off
	s_nop 0
	global_load_dwordx4 v[242:245], v[242:243], off
	s_nop 0
	global_load_dwordx4 v[246:249], v[246:247], off
	s_nop 0
	global_load_dwordx4 v[162:165], v[162:163], off
	s_nop 0
	s_nop 0
	s_nop 0
	s_nop 0
	s_nop 0
	s_nop 0
	s_nop 0
	s_nop 0
	s_nop 0
	s_nop 0
	s_nop 0
	s_nop 0
	s_nop 0
	s_nop 0
	s_nop 0
	s_nop 0
	s_nop 0
	s_nop 0
	s_nop 0
	s_nop 0
	s_nop 0
	s_nop 0
	s_nop 0
	s_nop 0
	s_nop 0
	s_nop 0
	s_nop 0
	s_nop 0
	s_nop 0
	s_nop 0
	s_nop 0
	s_nop 0
	s_nop 0
	s_nop 0
	s_nop 0
	s_nop 0
	s_nop 0
	s_nop 0
	s_nop 0
	s_nop 0
	s_nop 0
	s_nop 0
	s_nop 0
	s_nop 0
	s_nop 0
	s_nop 0
	s_nop 0
	s_nop 0
	s_nop 0
	s_nop 0
	s_nop 0
	s_nop 0
	s_nop 0
	s_nop 0
	global_load_dwordx4 v[66:69], v[2:3], off offset:160
	global_load_dwordx4 v[70:73], v[2:3], off offset:224
	global_load_dwordx4 v[92:95], v[2:3], off offset:128
	global_load_dwordx4 v[98:101], v[2:3], off offset:192
	global_load_dwordx4 v[108:111], v[2:3], off offset:32
	global_load_dwordx4 v[112:115], v[2:3], off offset:96
	global_load_dwordx4 v[116:119], v[2:3], off
	global_load_dwordx4 v[120:123], v[2:3], off offset:64
	global_load_dwordx4 v[58:61], v[182:183], off
	global_load_dwordx4 v[62:65], v[182:183], off offset:16
	global_load_dwordx4 v[50:53], v[182:183], off offset:64
	global_load_dwordx4 v[54:57], v[182:183], off offset:80
	global_load_dwordx4 v[42:45], v[182:183], off offset:128
	global_load_dwordx4 v[46:49], v[182:183], off offset:144
	global_load_dwordx4 v[34:37], v[182:183], off offset:192
	global_load_dwordx4 v[38:41], v[182:183], off offset:208
	global_load_dwordx4 v[26:29], v[182:183], off offset:256
	global_load_dwordx4 v[30:33], v[182:183], off offset:272
	global_load_dwordx4 v[18:21], v[182:183], off offset:336
	global_load_dwordx4 v[22:25], v[182:183], off offset:320
	global_load_dwordx4 v[10:13], v[182:183], off offset:384
	global_load_dwordx4 v[14:17], v[182:183], off offset:400
	global_load_dwordx4 v[2:5], v[182:183], off offset:464
	global_load_dwordx4 v[6:9], v[182:183], off offset:448
	s_cmp_lt_i32 s12, 0
	s_waitcnt vmcnt(0)
	v_and_b32_e32 v79, 0xffff0000, v67
	s_waitcnt vmcnt(22)
	v_and_b32_e32 v75, 0xffff0000, v71
	v_lshlrev_b32_e32 v74, 16, v71
	v_and_b32_e32 v77, 0xffff0000, v70
	v_lshlrev_b32_e32 v76, 16, v70
	s_waitcnt vmcnt(19)
	v_and_b32_e32 v127, 0xffff0000, v108
	s_waitcnt vmcnt(17)
	v_and_b32_e32 v71, 0xffff0000, v116
	v_lshlrev_b32_e32 v126, 16, v108
	v_lshlrev_b32_e32 v70, 16, v116
	v_mul_f32_e32 v108, v71, v71
	v_lshlrev_b32_e32 v78, 16, v67
	v_and_b32_e32 v83, 0xffff0000, v66
	v_lshlrev_b32_e32 v82, 16, v66
	v_and_b32_e32 v125, 0xffff0000, v109
	v_lshlrev_b32_e32 v124, 16, v109
	v_and_b32_e32 v131, 0xffff0000, v119
	v_lshlrev_b32_e32 v130, 16, v119
	s_waitcnt vmcnt(16)
	v_and_b32_e32 v133, 0xffff0000, v123
	v_lshlrev_b32_e32 v132, 16, v123
	v_and_b32_e32 v67, 0xffff0000, v118
	v_lshlrev_b32_e32 v66, 16, v118
	v_and_b32_e32 v119, 0xffff0000, v122
	v_lshlrev_b32_e32 v118, 16, v122
	v_and_b32_e32 v123, 0xffff0000, v117
	v_lshlrev_b32_e32 v122, 16, v117
	v_pk_fma_f32 v[108:109], v[70:71], v[70:71], v[108:109] op_sel_hi:[1,1,0]
	v_and_b32_e32 v107, 0xffff0000, v110
	v_lshlrev_b32_e32 v106, 16, v110
	v_pk_fma_f32 v[108:109], v[122:123], v[122:123], v[108:109]
	v_mul_f32_e32 v110, v123, v123
	v_pk_add_f32 v[108:109], v[110:111], v[108:109] op_sel_hi:[0,1]
	v_pk_fma_f32 v[108:109], v[66:67], v[66:67], v[108:109]
	v_mul_f32_e32 v110, v67, v67
	v_pk_add_f32 v[108:109], v[110:111], v[108:109] op_sel_hi:[0,1]
	v_pk_fma_f32 v[108:109], v[130:131], v[130:131], v[108:109]
	v_mul_f32_e32 v110, v131, v131
	v_pk_add_f32 v[108:109], v[110:111], v[108:109] op_sel_hi:[0,1]
	v_pk_fma_f32 v[108:109], v[126:127], v[126:127], v[108:109]
	v_mul_f32_e32 v110, v127, v127
	v_pk_add_f32 v[108:109], v[110:111], v[108:109] op_sel_hi:[0,1]
	v_pk_fma_f32 v[108:109], v[124:125], v[124:125], v[108:109]
	v_mul_f32_e32 v110, v125, v125
	v_pk_add_f32 v[108:109], v[110:111], v[108:109] op_sel_hi:[0,1]
	v_pk_fma_f32 v[108:109], v[106:107], v[106:107], v[108:109]
	v_mul_f32_e32 v110, v107, v107
	v_and_b32_e32 v81, 0xffff0000, v101
	v_lshlrev_b32_e32 v80, 16, v101
	v_and_b32_e32 v85, 0xffff0000, v100
	v_lshlrev_b32_e32 v84, 16, v100
	v_and_b32_e32 v101, 0xffff0000, v111
	v_lshlrev_b32_e32 v100, 16, v111
	v_pk_add_f32 v[108:109], v[110:111], v[108:109] op_sel_hi:[0,1]
	v_pk_fma_f32 v[108:109], v[100:101], v[100:101], v[108:109]
	v_mul_f32_e32 v110, v101, v101
	v_and_b32_e32 v135, 0xffff0000, v121
	v_lshlrev_b32_e32 v134, 16, v121
	v_and_b32_e32 v121, 0xffff0000, v120
	v_lshlrev_b32_e32 v120, 16, v120
	v_pk_add_f32 v[108:109], v[110:111], v[108:109] op_sel_hi:[0,1]
	v_pk_fma_f32 v[108:109], v[120:121], v[120:121], v[108:109]
	v_mul_f32_e32 v110, v121, v121
	v_pk_add_f32 v[108:109], v[110:111], v[108:109] op_sel_hi:[0,1]
	v_pk_fma_f32 v[108:109], v[134:135], v[134:135], v[108:109]
	v_mul_f32_e32 v110, v135, v135
	v_pk_add_f32 v[108:109], v[110:111], v[108:109] op_sel_hi:[0,1]
	v_pk_fma_f32 v[108:109], v[118:119], v[118:119], v[108:109]
	v_mul_f32_e32 v110, v119, v119
	v_pk_add_f32 v[108:109], v[110:111], v[108:109] op_sel_hi:[0,1]
	v_pk_fma_f32 v[108:109], v[132:133], v[132:133], v[108:109]
	v_mul_f32_e32 v110, v133, v133
	v_and_b32_e32 v129, 0xffff0000, v112
	v_lshlrev_b32_e32 v128, 16, v112
	v_pk_add_f32 v[108:109], v[110:111], v[108:109] op_sel_hi:[0,1]
	v_pk_fma_f32 v[108:109], v[128:129], v[128:129], v[108:109]
	v_mul_f32_e32 v110, v129, v129
	v_and_b32_e32 v105, 0xffff0000, v113
	v_lshlrev_b32_e32 v104, 16, v113
	v_pk_add_f32 v[108:109], v[110:111], v[108:109] op_sel_hi:[0,1]
	v_pk_fma_f32 v[108:109], v[104:105], v[104:105], v[108:109]
	v_mul_f32_e32 v110, v105, v105
	v_and_b32_e32 v103, 0xffff0000, v114
	v_lshlrev_b32_e32 v102, 16, v114
	v_pk_add_f32 v[108:109], v[110:111], v[108:109] op_sel_hi:[0,1]
	v_pk_fma_f32 v[108:109], v[102:103], v[102:103], v[108:109]
	v_mul_f32_e32 v110, v103, v103
	v_and_b32_e32 v87, 0xffff0000, v95
	v_lshlrev_b32_e32 v86, 16, v95
	v_and_b32_e32 v91, 0xffff0000, v94
	v_lshlrev_b32_e32 v90, 16, v94
	v_and_b32_e32 v95, 0xffff0000, v93
	v_lshlrev_b32_e32 v94, 16, v93
	v_and_b32_e32 v89, 0xffff0000, v99
	v_lshlrev_b32_e32 v88, 16, v99
	v_and_b32_e32 v97, 0xffff0000, v92
	v_lshlrev_b32_e32 v96, 16, v92
	v_and_b32_e32 v93, 0xffff0000, v98
	v_lshlrev_b32_e32 v92, 16, v98
	v_and_b32_e32 v99, 0xffff0000, v115
	v_lshlrev_b32_e32 v98, 16, v115
	v_pk_add_f32 v[108:109], v[110:111], v[108:109] op_sel_hi:[0,1]
	v_pk_fma_f32 v[108:109], v[98:99], v[98:99], v[108:109]
	v_mul_f32_e32 v110, v99, v99
	v_pk_add_f32 v[108:109], v[110:111], v[108:109] op_sel_hi:[0,1]
	v_pk_fma_f32 v[108:109], v[96:97], v[96:97], v[108:109]
	v_mul_f32_e32 v110, v97, v97
	v_pk_add_f32 v[108:109], v[110:111], v[108:109] op_sel_hi:[0,1]
	v_pk_fma_f32 v[108:109], v[94:95], v[94:95], v[108:109]
	v_mul_f32_e32 v110, v95, v95
	v_pk_add_f32 v[108:109], v[110:111], v[108:109] op_sel_hi:[0,1]
	v_pk_fma_f32 v[108:109], v[90:91], v[90:91], v[108:109]
	v_mul_f32_e32 v110, v91, v91
	v_pk_add_f32 v[108:109], v[110:111], v[108:109] op_sel_hi:[0,1]
	v_pk_fma_f32 v[108:109], v[86:87], v[86:87], v[108:109]
	v_mul_f32_e32 v110, v87, v87
	v_pk_add_f32 v[108:109], v[110:111], v[108:109] op_sel_hi:[0,1]
	v_pk_fma_f32 v[108:109], v[82:83], v[82:83], v[108:109]
	v_mul_f32_e32 v110, v83, v83
	v_pk_add_f32 v[108:109], v[110:111], v[108:109] op_sel_hi:[0,1]
	v_pk_fma_f32 v[108:109], v[78:79], v[78:79], v[108:109]
	v_mul_f32_e32 v110, v79, v79
	v_pk_add_f32 v[112:113], v[110:111], v[108:109] op_sel_hi:[0,1]
	v_and_b32_e32 v111, 0xffff0000, v72
	v_lshlrev_b32_e32 v110, 16, v68
	v_and_b32_e32 v109, 0xffff0000, v68
	v_pk_fma_f32 v[112:113], v[110:111], v[110:111], v[112:113]
	v_mul_f32_e32 v68, v109, v109
	v_pk_add_f32 v[136:137], v[68:69], v[112:113] op_sel_hi:[0,1]
	v_and_b32_e32 v115, 0xffff0000, v73
	v_lshlrev_b32_e32 v114, 16, v69
	v_and_b32_e32 v113, 0xffff0000, v69
	v_lshlrev_b32_e32 v108, 16, v72
	v_lshlrev_b32_e32 v112, 16, v73
	v_pk_fma_f32 v[72:73], v[114:115], v[114:115], v[136:137]
	v_mul_f32_e32 v136, v113, v113
	v_pk_add_f32 v[72:73], v[136:137], v[72:73] op_sel_hi:[0,1]
	v_pk_fma_f32 v[72:73], v[92:93], v[92:93], v[72:73]
	v_mul_f32_e32 v136, v93, v93
	v_pk_add_f32 v[72:73], v[136:137], v[72:73] op_sel_hi:[0,1]
	v_pk_fma_f32 v[72:73], v[88:89], v[88:89], v[72:73]
	v_mul_f32_e32 v136, v89, v89
	v_pk_add_f32 v[72:73], v[136:137], v[72:73] op_sel_hi:[0,1]
	v_pk_fma_f32 v[72:73], v[84:85], v[84:85], v[72:73]
	v_mul_f32_e32 v136, v85, v85
	v_pk_add_f32 v[72:73], v[136:137], v[72:73] op_sel_hi:[0,1]
	v_pk_fma_f32 v[72:73], v[80:81], v[80:81], v[72:73]
	v_mul_f32_e32 v136, v81, v81
	v_pk_add_f32 v[72:73], v[136:137], v[72:73] op_sel_hi:[0,1]
	v_pk_fma_f32 v[72:73], v[76:77], v[76:77], v[72:73]
	v_mul_f32_e32 v136, v77, v77
	v_pk_add_f32 v[72:73], v[136:137], v[72:73] op_sel_hi:[0,1]
	v_pk_mov_b32 v[116:117], v[110:111], v[108:109] op_sel:[1,0]
	v_pk_fma_f32 v[72:73], v[74:75], v[74:75], v[72:73]
	v_mul_f32_e32 v136, v75, v75
	v_pk_add_f32 v[72:73], v[136:137], v[72:73] op_sel_hi:[0,1]
	v_mul_f32_e32 v136, v117, v117
	v_pk_mov_b32 v[68:69], v[114:115], v[112:113] op_sel:[1,0]
	v_pk_add_f32 v[72:73], v[136:137], v[72:73] op_sel_hi:[0,1]
	v_pk_fma_f32 v[72:73], v[116:117], v[116:117], v[72:73]
	v_mul_f32_e32 v116, v69, v69
	v_pk_add_f32 v[72:73], v[116:117], v[72:73] op_sel_hi:[0,1]
	v_pk_fma_f32 v[68:69], v[68:69], v[68:69], v[72:73]
	s_waitcnt vmcnt(5)
	v_mov_b32_e32 v136, v18
	v_mov_b32_e32 v69, v68
	s_nop 1
	v_permlane32_swap_b32_e32 v68, v69
	v_add_f32_e32 v68, v68, v69
	v_fmamk_f32 v68, v68, 0x3c000000, v204
	v_mul_f32_e32 v69, 0x4b800000, v68
	v_cmp_gt_f32_e32 vcc, s49, v68
	s_waitcnt vmcnt(1)
	v_mov_b32_e32 v18, v2
	v_mov_b32_e32 v137, v3
	v_cndmask_b32_e32 v68, v68, v69, vcc
	v_rsq_f32_e32 v68, v68
	s_nop 0
	v_mul_f32_e32 v69, 0x45800000, v68
	v_cndmask_b32_e32 v68, v68, v69, vcc
	v_mul_f32_e32 v116, 0x3e0293ee, v68
	v_pk_mul_f32 v[58:59], v[58:59], v[116:117] op_sel_hi:[1,0]
	v_pk_mul_f32 v[62:63], v[62:63], v[116:117] op_sel_hi:[1,0]
	v_pk_mul_f32 v[70:71], v[58:59], v[70:71]
	v_pk_mul_f32 v[58:59], v[60:61], v[116:117] op_sel_hi:[1,0]
	v_pk_mul_f32 v[50:51], v[50:51], v[116:117] op_sel_hi:[1,0]
	v_pk_mul_f32 v[54:55], v[54:55], v[116:117] op_sel_hi:[1,0]
	v_pk_mul_f32 v[42:43], v[42:43], v[116:117] op_sel_hi:[1,0]
	v_pk_mul_f32 v[66:67], v[62:63], v[66:67]
	v_pk_mul_f32 v[72:73], v[58:59], v[122:123]
	v_pk_mul_f32 v[62:63], v[50:51], v[126:127]
	v_pk_mul_f32 v[58:59], v[54:55], v[106:107]
	v_pk_mul_f32 v[50:51], v[52:53], v[116:117] op_sel_hi:[1,0]
	v_pk_mul_f32 v[46:47], v[46:47], v[116:117] op_sel_hi:[1,0]
	v_pk_mul_f32 v[54:55], v[42:43], v[120:121]
	v_pk_mul_f32 v[42:43], v[44:45], v[116:117] op_sel_hi:[1,0]
	v_pk_mul_f32 v[34:35], v[34:35], v[116:117] op_sel_hi:[1,0]
	v_pk_mul_f32 v[38:39], v[38:39], v[116:117] op_sel_hi:[1,0]
	v_pk_mul_f32 v[26:27], v[26:27], v[116:117] op_sel_hi:[1,0]
	v_pk_mul_f32 v[60:61], v[64:65], v[116:117] op_sel_hi:[1,0]
	v_pk_mul_f32 v[52:53], v[56:57], v[116:117] op_sel_hi:[1,0]
	v_pk_mul_f32 v[64:65], v[50:51], v[124:125]
	v_pk_mul_f32 v[50:51], v[46:47], v[118:119]
	v_pk_mul_f32 v[56:57], v[42:43], v[134:135]
	v_pk_mul_f32 v[46:47], v[34:35], v[128:129]
	v_pk_mul_f32 v[42:43], v[38:39], v[102:103]
	v_pk_mul_f32 v[34:35], v[36:37], v[116:117] op_sel_hi:[1,0]
	v_pk_mul_f32 v[30:31], v[116:117], v[30:31] op_sel_hi:[0,1]
	v_pk_mul_f32 v[38:39], v[26:27], v[96:97]
	v_pk_mul_f32 v[26:27], v[28:29], v[116:117] op_sel_hi:[1,0]
	v_pk_mul_f32 v[22:23], v[116:117], v[22:23] op_sel_hi:[0,1]
	v_pk_mul_f32 v[10:11], v[116:117], v[10:11] op_sel_hi:[0,1]
	v_pk_mul_f32 v[44:45], v[48:49], v[116:117] op_sel_hi:[1,0]
	v_pk_mul_f32 v[36:37], v[40:41], v[116:117] op_sel_hi:[1,0]
	v_pk_mul_f32 v[48:49], v[34:35], v[104:105]
	v_pk_mul_f32 v[34:35], v[30:31], v[90:91]
	v_pk_mul_f32 v[28:29], v[116:117], v[32:33] op_sel_hi:[0,1]
	v_pk_mul_f32 v[40:41], v[26:27], v[94:95]
	v_pk_mul_f32 v[30:31], v[22:23], v[82:83]
	v_pk_mul_f32 v[18:19], v[116:117], v[18:19] op_sel_hi:[0,1]
	v_pk_mul_f32 v[22:23], v[116:117], v[24:25] op_sel_hi:[0,1]
	v_mov_b32_e32 v24, v20
	v_mov_b32_e32 v25, v5
	v_mov_b32_e32 v20, v4
	v_pk_mul_f32 v[26:27], v[10:11], v[92:93]
	v_pk_mul_f32 v[10:11], v[116:117], v[12:13] op_sel_hi:[0,1]
	v_pk_mul_f32 v[12:13], v[116:117], v[16:17] op_sel_hi:[0,1]
	s_waitcnt vmcnt(0)
	v_pk_mul_f32 v[6:7], v[116:117], v[6:7] op_sel_hi:[0,1]
	v_pk_mul_f32 v[32:33], v[28:29], v[86:87]
	v_pk_mul_f32 v[86:87], v[116:117], v[136:137] op_sel_hi:[0,1]
	v_pk_mul_f32 v[82:83], v[116:117], v[24:25] op_sel_hi:[0,1]
	v_pk_mul_f32 v[20:21], v[116:117], v[20:21] op_sel_hi:[0,1]
	v_pk_mul_f32 v[14:15], v[116:117], v[14:15] op_sel_hi:[0,1]
	v_pk_mul_f32 v[24:25], v[12:13], v[80:81]
	v_pk_mul_f32 v[80:81], v[18:19], v[108:109]
	v_pk_mul_f32 v[18:19], v[6:7], v[76:77]
	v_pk_mul_f32 v[6:7], v[116:117], v[8:9] op_sel_hi:[0,1]
	v_pk_mul_f32 v[68:69], v[60:61], v[130:131]
	v_pk_mul_f32 v[60:61], v[52:53], v[100:101]
	v_pk_mul_f32 v[52:53], v[44:45], v[132:133]
	v_pk_mul_f32 v[44:45], v[36:37], v[98:99]
	v_pk_mul_f32 v[36:37], v[22:23], v[78:79]
	v_pk_mul_f32 v[22:23], v[14:15], v[84:85]
	v_pk_mul_f32 v[28:29], v[10:11], v[88:89]
	v_pk_mul_f32 v[78:79], v[86:87], v[110:111]
	v_pk_mul_f32 v[76:77], v[20:21], v[112:113]
	v_pk_mul_f32 v[20:21], v[6:7], v[74:75]
	v_pk_mul_f32 v[74:75], v[82:83], v[114:115]
	s_cbranch_scc1 .LBB0_284
	v_add_u32_e32 v90, s12, v221
	v_ashrrev_i32_e32 v2, 1, v90
	v_and_b32_e32 v2, 0xffffffe0, v2
	v_ashrrev_i32_e32 v3, 31, v2
	v_lshl_add_u64 v[86:87], v[2:3], 3, v[192:193]
	global_load_dwordx4 v[2:5], v[86:87], off offset:48
	global_load_dwordx4 v[6:9], v[86:87], off offset:32
	global_load_dwordx4 v[10:13], v[86:87], off offset:16
	global_load_dwordx4 v[14:17], v[86:87], off
	v_pk_mov_b32 v[84:85], v[80:81], v[78:79] op_sel:[1,0]
	v_pk_mov_b32 v[82:83], v[76:77], v[74:75] op_sel:[1,0]
	s_waitcnt vmcnt(0)
	v_mov_b32_e32 v89, v16
	v_mov_b32_e32 v16, v15
	v_mov_b32_e32 v88, v14
	v_pk_mul_f32 v[14:15], v[70:71], v[16:17]
	v_pk_mul_f32 v[16:17], v[54:55], v[16:17]
	v_pk_fma_f32 v[54:55], v[54:55], v[88:89], v[14:15]
	v_mov_b32_e32 v15, v12
	v_mov_b32_e32 v12, v11
	v_mov_b32_e32 v14, v10
	v_pk_mul_f32 v[10:11], v[72:73], v[12:13]
	v_pk_mul_f32 v[12:13], v[56:57], v[12:13]
	v_pk_fma_f32 v[56:57], v[56:57], v[14:15], v[10:11]
	v_mov_b32_e32 v11, v8
	v_mov_b32_e32 v8, v7
	v_mov_b32_e32 v10, v6
	v_pk_mul_f32 v[6:7], v[66:67], v[8:9]
	v_pk_mul_f32 v[8:9], v[50:51], v[8:9]
	v_pk_fma_f32 v[50:51], v[50:51], v[10:11], v[6:7]
	v_mov_b32_e32 v7, v4
	v_mov_b32_e32 v4, v3
	v_mov_b32_e32 v6, v2
	v_pk_mul_f32 v[2:3], v[68:69], v[4:5]
	v_pk_mul_f32 v[4:5], v[52:53], v[4:5]
	v_pk_fma_f32 v[70:71], v[70:71], v[88:89], v[16:17] neg_lo:[0,0,1] neg_hi:[0,0,1]
	v_pk_fma_f32 v[72:73], v[72:73], v[14:15], v[12:13] neg_lo:[0,0,1] neg_hi:[0,0,1]
	v_pk_fma_f32 v[66:67], v[66:67], v[10:11], v[8:9] neg_lo:[0,0,1] neg_hi:[0,0,1]
	v_pk_fma_f32 v[68:69], v[68:69], v[6:7], v[4:5] neg_lo:[0,0,1] neg_hi:[0,0,1]
	v_pk_fma_f32 v[52:53], v[52:53], v[6:7], v[2:3]
	global_load_dwordx4 v[2:5], v[86:87], off offset:176
	global_load_dwordx4 v[6:9], v[86:87], off offset:160
	global_load_dwordx4 v[10:13], v[86:87], off offset:144
	global_load_dwordx4 v[14:17], v[86:87], off offset:128
	s_waitcnt vmcnt(0)
	v_mov_b32_e32 v87, v16
	v_mov_b32_e32 v16, v15
	v_mov_b32_e32 v86, v14
	v_pk_mul_f32 v[14:15], v[62:63], v[16:17]
	v_pk_mul_f32 v[16:17], v[46:47], v[16:17]
	v_pk_fma_f32 v[46:47], v[46:47], v[86:87], v[14:15]
	v_mov_b32_e32 v15, v12
	v_mov_b32_e32 v12, v11
	v_mov_b32_e32 v14, v10
	v_pk_mul_f32 v[10:11], v[64:65], v[12:13]
	v_pk_mul_f32 v[12:13], v[48:49], v[12:13]
	v_pk_fma_f32 v[48:49], v[48:49], v[14:15], v[10:11]
	v_mov_b32_e32 v11, v8
	v_mov_b32_e32 v8, v7
	v_mov_b32_e32 v10, v6
	v_pk_mul_f32 v[6:7], v[58:59], v[8:9]
	v_pk_mul_f32 v[8:9], v[42:43], v[8:9]
	v_pk_fma_f32 v[42:43], v[42:43], v[10:11], v[6:7]
	v_mov_b32_e32 v7, v4
	v_mov_b32_e32 v4, v3
	v_mov_b32_e32 v6, v2
	v_pk_mul_f32 v[2:3], v[60:61], v[4:5]
	v_pk_mul_f32 v[4:5], v[44:45], v[4:5]
	v_pk_fma_f32 v[44:45], v[44:45], v[6:7], v[2:3]
	v_lshlrev_b32_e32 v2, 8, v90
	v_and_b32_e32 v2, 0x3f00, v2
	v_mov_b32_e32 v3, v1
	v_pk_fma_f32 v[62:63], v[62:63], v[86:87], v[16:17] neg_lo:[0,0,1] neg_hi:[0,0,1]
	v_lshl_add_u64 v[86:87], v[192:193], 0, v[2:3]
	v_pk_fma_f32 v[64:65], v[64:65], v[14:15], v[12:13] neg_lo:[0,0,1] neg_hi:[0,0,1]
	v_pk_fma_f32 v[58:59], v[58:59], v[10:11], v[8:9] neg_lo:[0,0,1] neg_hi:[0,0,1]
	v_pk_fma_f32 v[60:61], v[60:61], v[6:7], v[4:5] neg_lo:[0,0,1] neg_hi:[0,0,1]
	global_load_dwordx4 v[2:5], v[86:87], off offset:48
	global_load_dwordx4 v[6:9], v[86:87], off offset:32
	global_load_dwordx4 v[10:13], v[86:87], off offset:16
	global_load_dwordx4 v[14:17], v[86:87], off
	s_waitcnt vmcnt(0)
	v_mov_b32_e32 v89, v16
	v_mov_b32_e32 v16, v15
	v_mov_b32_e32 v88, v14
	v_pk_mul_f32 v[14:15], v[38:39], v[16:17]
	v_pk_mul_f32 v[16:17], v[26:27], v[16:17]
	v_pk_fma_f32 v[26:27], v[26:27], v[88:89], v[14:15]
	v_mov_b32_e32 v15, v12
	v_mov_b32_e32 v12, v11
	v_mov_b32_e32 v14, v10
	v_pk_mul_f32 v[10:11], v[40:41], v[12:13]
	v_pk_mul_f32 v[12:13], v[28:29], v[12:13]
	v_pk_fma_f32 v[28:29], v[28:29], v[14:15], v[10:11]
	v_mov_b32_e32 v11, v8
	v_mov_b32_e32 v8, v7
	v_mov_b32_e32 v10, v6
	v_pk_mul_f32 v[6:7], v[34:35], v[8:9]
	v_pk_mul_f32 v[8:9], v[22:23], v[8:9]
	v_pk_fma_f32 v[22:23], v[22:23], v[10:11], v[6:7]
	v_mov_b32_e32 v7, v4
	v_mov_b32_e32 v4, v3
	v_mov_b32_e32 v6, v2
	v_pk_mul_f32 v[2:3], v[32:33], v[4:5]
	v_pk_mul_f32 v[4:5], v[24:25], v[4:5]
	v_pk_fma_f32 v[38:39], v[38:39], v[88:89], v[16:17] neg_lo:[0,0,1] neg_hi:[0,0,1]
	v_pk_fma_f32 v[40:41], v[40:41], v[14:15], v[12:13] neg_lo:[0,0,1] neg_hi:[0,0,1]
	v_pk_fma_f32 v[34:35], v[34:35], v[10:11], v[8:9] neg_lo:[0,0,1] neg_hi:[0,0,1]
	v_pk_fma_f32 v[32:33], v[32:33], v[6:7], v[4:5] neg_lo:[0,0,1] neg_hi:[0,0,1]
	v_pk_fma_f32 v[24:25], v[24:25], v[6:7], v[2:3]
	global_load_dwordx4 v[2:5], v[86:87], off offset:176
	global_load_dwordx4 v[6:9], v[86:87], off offset:160
	global_load_dwordx4 v[10:13], v[86:87], off offset:144
	global_load_dwordx4 v[14:17], v[86:87], off offset:128
	s_waitcnt vmcnt(3)
	v_mov_b32_e32 v88, v3
	s_waitcnt vmcnt(2)
	v_mov_b32_e32 v86, v7
	v_mov_b32_e32 v87, v8
	s_waitcnt vmcnt(0)
	v_mov_b32_e32 v91, v16
	v_mov_b32_e32 v16, v15
	v_mov_b32_e32 v90, v14
	v_pk_mul_f32 v[14:15], v[30:31], v[16:17]
	v_pk_mul_f32 v[16:17], v[18:19], v[16:17]
	v_pk_fma_f32 v[18:19], v[18:19], v[90:91], v[14:15]
	v_mov_b32_e32 v15, v12
	v_mov_b32_e32 v12, v11
	v_mov_b32_e32 v14, v10
	v_pk_mul_f32 v[10:11], v[36:37], v[12:13]
	v_pk_mul_f32 v[12:13], v[20:21], v[12:13]
	v_pk_fma_f32 v[20:21], v[20:21], v[14:15], v[10:11]
	v_pk_fma_f32 v[36:37], v[36:37], v[14:15], v[12:13] neg_lo:[0,0,1] neg_hi:[0,0,1]
	v_pk_mov_b32 v[14:15], v[86:87], v[86:87] op_sel:[1,0]
	v_mov_b32_e32 v7, v9
	v_pk_mov_b32 v[12:13], v[78:79], v[80:81] op_sel:[1,0]
	v_mov_b32_e32 v8, v9
	v_mov_b32_e32 v9, v15
	v_mov_b32_e32 v89, v4
	v_pk_mul_f32 v[8:9], v[12:13], v[8:9]
	v_mov_b32_e32 v15, v6
	v_pk_fma_f32 v[8:9], v[84:85], v[14:15], v[8:9] neg_lo:[0,0,1] neg_hi:[0,0,1]
	v_pk_mov_b32 v[14:15], v[88:89], v[88:89] op_sel:[1,0]
	v_mov_b32_e32 v3, v5
	v_pk_mov_b32 v[12:13], v[74:75], v[76:77] op_sel:[1,0]
	v_mov_b32_e32 v4, v5
	v_mov_b32_e32 v5, v15
	v_pk_mul_f32 v[10:11], v[80:81], v[6:7]
	v_pk_mul_f32 v[4:5], v[12:13], v[4:5]
	v_mov_b32_e32 v15, v2
	v_pk_fma_f32 v[6:7], v[78:79], v[86:87], v[10:11]
	v_pk_mul_f32 v[10:11], v[76:77], v[2:3]
	v_pk_fma_f32 v[4:5], v[82:83], v[14:15], v[4:5] neg_lo:[0,0,1] neg_hi:[0,0,1]
	v_pk_fma_f32 v[30:31], v[30:31], v[90:91], v[16:17] neg_lo:[0,0,1] neg_hi:[0,0,1]
	v_pk_fma_f32 v[2:3], v[74:75], v[88:89], v[10:11]
	v_mov_b32_e32 v77, v4
	v_mov_b32_e32 v74, v5
	v_mov_b32_e32 v81, v8
	v_mov_b32_e32 v78, v9
	s_branch .LBB0_285

.LBB0_285:
	s_lshl_b32 s11, s11, 6
	s_and_b32 s11, s11, 0x100
	s_add_u32 s12, s18, s11
	s_addc_u32 s13, s19, 0
	s_add_u32 s14, s20, s11
	s_addc_u32 s15, s21, 0
	s_ashr_i32 s11, s10, 31
	v_cvt_pk_bf16_f32 v134, v70, v71
	v_cvt_pk_bf16_f32 v135, v72, v73
	v_cvt_pk_bf16_f32 v136, v66, v67
	v_cvt_pk_bf16_f32 v137, v68, v69
	v_cvt_pk_bf16_f32 v142, v62, v63
	v_cvt_pk_bf16_f32 v143, v64, v65
	v_cvt_pk_bf16_f32 v144, v58, v59
	v_cvt_pk_bf16_f32 v145, v60, v61
	v_cvt_pk_bf16_f32 v146, v54, v55
	v_cvt_pk_bf16_f32 v147, v56, v57
	v_cvt_pk_bf16_f32 v148, v50, v51
	v_cvt_pk_bf16_f32 v149, v52, v53
	v_cvt_pk_bf16_f32 v150, v46, v47
	v_cvt_pk_bf16_f32 v151, v48, v49
	v_cvt_pk_bf16_f32 v152, v42, v43
	v_cvt_pk_bf16_f32 v153, v44, v45
	v_cvt_pk_bf16_f32 v154, v38, v39
	v_cvt_pk_bf16_f32 v155, v40, v41
	v_cvt_pk_bf16_f32 v156, v34, v35
	v_cvt_pk_bf16_f32 v157, v32, v33
	v_cvt_pk_bf16_f32 v158, v30, v31
	v_cvt_pk_bf16_f32 v159, v36, v37
	v_cvt_pk_bf16_f32 v160, v78, v81
	v_cvt_pk_bf16_f32 v161, v74, v77
	v_cvt_pk_bf16_f32 v138, v26, v27
	v_cvt_pk_bf16_f32 v139, v28, v29
	v_cvt_pk_bf16_f32 v140, v22, v23
	v_cvt_pk_bf16_f32 v141, v24, v25
	v_cvt_pk_bf16_f32 v130, v18, v19
	v_cvt_pk_bf16_f32 v131, v20, v21
	v_cvt_pk_bf16_f32 v132, v6, v7
	v_cvt_pk_bf16_f32 v133, v2, v3
	v_mov_b32_e32 v195, v1
	v_lshl_add_u64 v[198:199], s[12:13], 0, v[194:195]
	s_or_b32 s12, s10, 64
	s_ashr_i32 s13, s12, 31
	v_add_u32_e32 v62, 16, v222
	v_lshl_add_u64 v[200:201], s[14:15], 0, v[194:195]
	v_lshl_add_u64 v[18:19], s[12:13], 0, v[184:185]
	v_add_u32_e32 v63, 16, v223
	v_add_u32_e32 v64, 16, v224
	v_add_u32_e32 v67, 16, v225
	v_lshl_add_u64 v[20:21], v[186:187], 0, s[12:13]
	v_mad_u64_u32 v[22:23], s[12:13], v18, s65, v[198:199]
	s_waitcnt vmcnt(0)
	v_mad_u64_u32 v[24:25], s[12:13], v20, s65, v[198:199]
	v_mad_i32_i24 v23, v19, s65, v23
	v_mad_i32_i24 v25, v21, s65, v25
	s_waitcnt vmcnt(3)
	ds_write_b128 v62, v[238:241]
	s_waitcnt vmcnt(2)
	ds_write_b128 v63, v[242:245]
	s_waitcnt vmcnt(1)
	ds_write_b128 v64, v[246:249] offset:32768
	s_waitcnt vmcnt(0)
	ds_write_b128 v67, v[162:165] offset:32768
	v_mad_u64_u32 v[2:3], s[12:13], v18, s65, v[200:201]
	v_mad_i32_i24 v3, v19, s65, v3
	v_mad_u64_u32 v[4:5], s[12:13], v20, s65, v[200:201]
	s_waitcnt lgkmcnt(0)
	s_barrier
	global_load_dwordx4 v[50:53], v[22:23], off
	global_load_dwordx4 v[68:71], v[24:25], off
	v_mad_i32_i24 v5, v21, s65, v5
	global_load_dwordx4 v[54:57], v[2:3], off
	global_load_dwordx4 v[58:61], v[4:5], off
	v_add_u32_e32 v6, v227, v228
	ds_read_b128 v[2:5], v6 offset:32768
	ds_read_b128 v[18:21], v6 offset:40960
	v_add_u32_e32 v38, v227, v229
	ds_read_b128 v[34:37], v38 offset:32768
	ds_read_b128 v[38:41], v38 offset:40960
	s_waitcnt lgkmcnt(3)
	v_mfma_f32_32x32x16_bf16 v[2:17], v[2:5], v[134:137], 0
	s_waitcnt lgkmcnt(2)
	v_mfma_f32_32x32x16_bf16 v[18:33], v[18:21], v[134:137], 0
	s_waitcnt lgkmcnt(1)
	v_mfma_f32_32x32x16_bf16 v[2:17], v[34:37], v[142:145], v[2:17]
	s_waitcnt lgkmcnt(0)
	v_mfma_f32_32x32x16_bf16 v[18:33], v[38:41], v[142:145], v[18:33]
	v_add_u32_e32 v38, v227, v230
	ds_read_b128 v[34:37], v38 offset:32768
	ds_read_b128 v[38:41], v38 offset:40960
	s_waitcnt lgkmcnt(1)
	v_mfma_f32_32x32x16_bf16 v[2:17], v[34:37], v[146:149], v[2:17]
	s_waitcnt lgkmcnt(0)
	v_mfma_f32_32x32x16_bf16 v[18:33], v[38:41], v[146:149], v[18:33]
	v_add_u32_e32 v38, v227, v231
	ds_read_b128 v[34:37], v38 offset:32768
	ds_read_b128 v[38:41], v38 offset:40960
	s_waitcnt lgkmcnt(1)
	v_mfma_f32_32x32x16_bf16 v[2:17], v[34:37], v[150:153], v[2:17]
	s_waitcnt lgkmcnt(0)
	v_mfma_f32_32x32x16_bf16 v[18:33], v[38:41], v[150:153], v[18:33]
	v_add_u32_e32 v38, v227, v232
	ds_read_b128 v[34:37], v38 offset:32768
	ds_read_b128 v[38:41], v38 offset:40960
	s_waitcnt lgkmcnt(1)
	v_mfma_f32_32x32x16_bf16 v[2:17], v[34:37], v[154:157], v[2:17]
	s_waitcnt lgkmcnt(0)
	v_mfma_f32_32x32x16_bf16 v[18:33], v[38:41], v[154:157], v[18:33]
	v_add_u32_e32 v38, v227, v233
	ds_read_b128 v[34:37], v38 offset:32768
	ds_read_b128 v[38:41], v38 offset:40960
	s_waitcnt lgkmcnt(1)
	v_mfma_f32_32x32x16_bf16 v[2:17], v[34:37], v[158:161], v[2:17]
	s_waitcnt lgkmcnt(0)
	v_mfma_f32_32x32x16_bf16 v[18:33], v[38:41], v[158:161], v[18:33]
	v_add_u32_e32 v38, v227, v234
	ds_read_b128 v[34:37], v38 offset:32768
	ds_read_b128 v[38:41], v38 offset:40960
	s_waitcnt lgkmcnt(1)
	v_mfma_f32_32x32x16_bf16 v[2:17], v[34:37], v[138:141], v[2:17]
	s_waitcnt lgkmcnt(0)
	v_mfma_f32_32x32x16_bf16 v[18:33], v[38:41], v[138:141], v[18:33]
	v_add_u32_e32 v38, v227, v235
	ds_read_b128 v[34:37], v38 offset:32768
	ds_read_b128 v[38:41], v38 offset:40960
	s_waitcnt lgkmcnt(1)
	v_mfma_f32_32x32x16_bf16 v[2:17], v[34:37], v[130:133], v[2:17]
	s_waitcnt lgkmcnt(0)
	v_mfma_f32_32x32x16_bf16 v[18:33], v[38:41], v[130:133], v[18:33]
	s_nop 9
	s_nop 0
	s_nop 0
	v_max_f32_e32 v34, v3, v2
	v_max3_f32 v34, v34, v4, v5
	v_max3_f32 v34, v34, v6, v7
	v_max3_f32 v34, v34, v8, v9
	v_max3_f32 v34, v34, v10, v11
	v_max3_f32 v34, v34, v12, v13
	v_max3_f32 v34, v34, v14, v15
	v_max3_f32 v34, v34, v16, v17
	v_max3_f32 v34, v34, v18, v19
	v_max3_f32 v34, v34, v20, v21
	v_max3_f32 v34, v34, v22, v23
	v_max3_f32 v34, v34, v24, v25
	v_max3_f32 v34, v34, v26, v27
	v_max3_f32 v34, v34, v28, v29
	v_max3_f32 v34, v34, v30, v31
	v_max3_f32 v34, v34, v32, v33
	v_mov_b32_e32 v35, v34
	s_nop 1
	v_permlane32_swap_b32_e32 v34, v35
	s_nop 0
	s_nop 0
	v_max_f32_e32 v35, v35, v34
	v_sub_f32_e32 v2, v2, v35
	v_sub_f32_e32 v3, v3, v35
	v_exp_f32_e32 v2, v2
	v_sub_f32_e32 v4, v4, v35
	v_exp_f32_e32 v3, v3
	v_sub_f32_e32 v5, v5, v35
	v_exp_f32_e32 v4, v4
	v_sub_f32_e32 v6, v6, v35
	v_exp_f32_e32 v5, v5
	v_sub_f32_e32 v7, v7, v35
	v_exp_f32_e32 v6, v6
	v_add_f32_e32 v34, 0, v2
	v_sub_f32_e32 v8, v8, v35
	v_exp_f32_e32 v7, v7
	v_add_f32_e32 v34, v3, v34
	v_sub_f32_e32 v9, v9, v35
	v_exp_f32_e32 v8, v8
	v_add_f32_e32 v34, v4, v34
	v_sub_f32_e32 v10, v10, v35
	v_exp_f32_e32 v9, v9
	v_add_f32_e32 v34, v5, v34
	v_sub_f32_e32 v11, v11, v35
	v_exp_f32_e32 v10, v10
	v_add_f32_e32 v34, v6, v34
	v_sub_f32_e32 v12, v12, v35
	v_exp_f32_e32 v11, v11
	v_add_f32_e32 v34, v7, v34
	v_sub_f32_e32 v13, v13, v35
	v_exp_f32_e32 v12, v12
	v_add_f32_e32 v34, v8, v34
	v_sub_f32_e32 v14, v14, v35
	v_exp_f32_e32 v13, v13
	v_add_f32_e32 v34, v9, v34
	v_sub_f32_e32 v15, v15, v35
	v_exp_f32_e32 v14, v14
	v_add_f32_e32 v34, v10, v34
	v_sub_f32_e32 v16, v16, v35
	v_exp_f32_e32 v15, v15
	v_add_f32_e32 v34, v11, v34
	v_sub_f32_e32 v17, v17, v35
	v_exp_f32_e32 v16, v16
	v_add_f32_e32 v34, v12, v34
	v_sub_f32_e32 v18, v18, v35
	v_exp_f32_e32 v17, v17
	v_add_f32_e32 v34, v13, v34
	v_sub_f32_e32 v19, v19, v35
	v_exp_f32_e32 v18, v18
	v_add_f32_e32 v34, v14, v34
	v_sub_f32_e32 v20, v20, v35
	v_exp_f32_e32 v19, v19
	v_add_f32_e32 v34, v15, v34
	v_sub_f32_e32 v21, v21, v35
	v_exp_f32_e32 v20, v20
	v_add_f32_e32 v34, v16, v34
	v_sub_f32_e32 v22, v22, v35
	v_exp_f32_e32 v21, v21
	v_add_f32_e32 v34, v17, v34
	v_sub_f32_e32 v23, v23, v35
	v_exp_f32_e32 v22, v22
	v_add_f32_e32 v34, v18, v34
	v_sub_f32_e32 v24, v24, v35
	v_exp_f32_e32 v23, v23
	v_add_f32_e32 v34, v19, v34
	v_sub_f32_e32 v25, v25, v35
	v_exp_f32_e32 v24, v24
	v_add_f32_e32 v34, v20, v34
	v_sub_f32_e32 v26, v26, v35
	v_exp_f32_e32 v25, v25
	v_add_f32_e32 v34, v21, v34
	v_sub_f32_e32 v27, v27, v35
	v_exp_f32_e32 v26, v26
	v_add_f32_e32 v34, v22, v34
	v_sub_f32_e32 v28, v28, v35
	v_exp_f32_e32 v27, v27
	v_add_f32_e32 v34, v23, v34
	v_sub_f32_e32 v29, v29, v35
	v_exp_f32_e32 v28, v28
	v_add_f32_e32 v34, v24, v34
	v_sub_f32_e32 v30, v30, v35
	v_exp_f32_e32 v29, v29
	v_add_f32_e32 v34, v25, v34
	v_sub_f32_e32 v31, v31, v35
	v_exp_f32_e32 v30, v30
	v_add_f32_e32 v34, v26, v34
	v_sub_f32_e32 v32, v32, v35
	v_exp_f32_e32 v31, v31
	v_add_f32_e32 v34, v27, v34
	v_sub_f32_e32 v33, v33, v35
	v_exp_f32_e32 v32, v32
	v_add_f32_e32 v34, v28, v34
	v_exp_f32_e32 v33, v33
	v_add_f32_e32 v34, v29, v34
	v_add_f32_e32 v34, v30, v34
	v_add_f32_e32 v34, v31, v34
	v_add_f32_e32 v34, v32, v34
	v_add_f32_e32 v34, v33, v34
	v_mov_b32_e32 v36, v34
	s_nop 1
	v_permlane32_swap_b32_e32 v34, v36
	v_add_f32_e32 v34, v34, v36
	v_pk_add_f32 v[202:203], v[34:35], 0 op_sel_hi:[1,0]
	v_cvt_pk_bf16_f32 v72, v2, v3
	v_cvt_pk_bf16_f32 v73, v4, v5
	v_cvt_pk_bf16_f32 v74, v6, v7
	v_cvt_pk_bf16_f32 v75, v8, v9
	v_cvt_pk_bf16_f32 v76, v10, v11
	s_nop 0
	v_xor_b32_e32 v66, 0x80000000, v203
	v_cvt_pk_bf16_f32 v77, v12, v13
	v_cvt_pk_bf16_f32 v78, v14, v15
	v_cvt_pk_bf16_f32 v79, v16, v17
	v_cvt_pk_bf16_f32 v80, v18, v19
	v_cvt_pk_bf16_f32 v81, v20, v21
	v_cvt_pk_bf16_f32 v82, v22, v23
	v_cvt_pk_bf16_f32 v83, v24, v25
	v_cvt_pk_bf16_f32 v84, v26, v27
	v_cvt_pk_bf16_f32 v85, v28, v29
	v_cvt_pk_bf16_f32 v86, v30, v31
	v_cvt_pk_bf16_f32 v87, v32, v33
	ds_read_b64_tr_b16 v[2:3], v237 offset:0
	ds_read_b64_tr_b16 v[4:5], v237 offset:0x800
	ds_read_b64_tr_b16 v[18:19], v237 offset:0x1000
	ds_read_b64_tr_b16 v[20:21], v237 offset:0x1800
	ds_read_b64_tr_b16 v[22:23], v237 offset:0x2000
	ds_read_b64_tr_b16 v[24:25], v237 offset:0x2800
	ds_read_b64_tr_b16 v[26:27], v237 offset:0x3000
	ds_read_b64_tr_b16 v[28:29], v237 offset:0x3800
	s_waitcnt lgkmcnt(0)
	s_nop 0
	v_mfma_f32_32x32x16_bf16 v[2:17], v[72:75], v[2:5], 0
	v_mfma_f32_32x32x16_bf16 v[2:17], v[76:79], v[18:21], v[2:17]
	ds_read_b64_tr_b16 v[18:19], v237 offset:0x200
	ds_read_b64_tr_b16 v[20:21], v237 offset:0xa00
	ds_read_b64_tr_b16 v[34:35], v237 offset:0x1200
	ds_read_b64_tr_b16 v[36:37], v237 offset:0x1a00
	ds_read_b64_tr_b16 v[38:39], v237 offset:0x2200
	ds_read_b64_tr_b16 v[40:41], v237 offset:0x2a00
	ds_read_b64_tr_b16 v[42:43], v237 offset:0x3200
	v_mfma_f32_32x32x16_bf16 v[2:17], v[80:83], v[22:25], v[2:17]
	ds_read_b64_tr_b16 v[44:45], v237 offset:0x3a00
	s_waitcnt lgkmcnt(0)
	v_mfma_f32_32x32x16_bf16 v[2:17], v[84:87], v[26:29], v[2:17]
	v_mfma_f32_32x32x16_bf16 v[18:33], v[72:75], v[18:21], 0
	v_mfma_f32_32x32x16_bf16 v[18:33], v[76:79], v[34:37], v[18:33]
	ds_read_b64_tr_b16 v[34:35], v237 offset:0x400
	ds_read_b64_tr_b16 v[36:37], v237 offset:0xc00
	ds_read_b64_tr_b16 v[88:89], v237 offset:0x1400
	ds_read_b64_tr_b16 v[90:91], v237 offset:0x1c00
	ds_read_b64_tr_b16 v[92:93], v237 offset:0x2400
	ds_read_b64_tr_b16 v[94:95], v237 offset:0x2c00
	ds_read_b64_tr_b16 v[96:97], v237 offset:0x3400
	v_mfma_f32_32x32x16_bf16 v[18:33], v[80:83], v[38:41], v[18:33]
	ds_read_b64_tr_b16 v[98:99], v237 offset:0x3c00
	s_waitcnt lgkmcnt(0)
	v_mfma_f32_32x32x16_bf16 v[18:33], v[84:87], v[42:45], v[18:33]
	v_mfma_f32_32x32x16_bf16 v[34:49], v[72:75], v[34:37], 0
	v_mfma_f32_32x32x16_bf16 v[34:49], v[76:79], v[88:91], v[34:49]
	ds_read_b64_tr_b16 v[88:89], v237 offset:0x600
	ds_read_b64_tr_b16 v[90:91], v237 offset:0xe00
	v_mfma_f32_32x32x16_bf16 v[34:49], v[80:83], v[92:95], v[34:49]
	ds_read_b64_tr_b16 v[92:93], v237 offset:0x1600
	ds_read_b64_tr_b16 v[94:95], v237 offset:0x1e00
	v_mfma_f32_32x32x16_bf16 v[34:49], v[84:87], v[96:99], v[34:49]
	ds_read_b64_tr_b16 v[96:97], v237 offset:0x2600
	ds_read_b64_tr_b16 v[98:99], v237 offset:0x2e00
	ds_read_b64_tr_b16 v[100:101], v237 offset:0x3600
	ds_read_b64_tr_b16 v[102:103], v237 offset:0x3e00
	s_waitcnt lgkmcnt(0)
	s_waitcnt vmcnt(1)
	ds_write_b128 v62, v[54:57] offset:16384
	s_waitcnt vmcnt(0)
	ds_write_b128 v63, v[58:61] offset:16384
	ds_write_b128 v64, v[50:53] offset:49152
	v_mfma_f32_32x32x16_bf16 v[50:65], v[72:75], v[88:91], 0
	ds_write_b128 v67, v[68:71] offset:49152
	s_addk_i32 s10, 0x80
	s_mov_b32 s14, 0
	s_movk_i32 s15, 0x4000
	v_mov_b32_e32 v67, v66
	v_mov_b32_e32 v68, v66
	v_mov_b32_e32 v69, v66
	v_mfma_f32_32x32x16_bf16 v[50:65], v[76:79], v[92:95], v[50:65]
	v_mov_b32_e32 v70, v66
	v_mov_b32_e32 v71, v66
	v_mov_b32_e32 v72, v66
	v_mov_b32_e32 v73, v66
	v_mov_b32_e32 v74, v66
	v_mov_b32_e32 v75, v66
	v_mov_b32_e32 v76, v66
	v_mfma_f32_32x32x16_bf16 v[50:65], v[80:83], v[96:99], v[50:65]
	v_mov_b32_e32 v77, v66
	v_mov_b32_e32 v78, v66
	v_mov_b32_e32 v79, v66
	v_mov_b32_e32 v80, v66
	v_mov_b32_e32 v81, v66
	s_waitcnt lgkmcnt(0)
	s_barrier
	v_mfma_f32_32x32x16_bf16 v[50:65], v[84:87], v[100:103], v[50:65]
	s_and_b32 s24, s22, 7
	s_lshl_b32 s24, s24, 6
	s_and_b32 s24, s24, 0x100
	s_mul_i32 s25, s10, 0x1400
	s_add_u32 s24, s24, s25
	s_add_u32 s24, s18, s24
	s_addc_u32 s25, s19, 0
	v_readlane_b32 s26, v254, 10
	s_nop 3
	s_lshl_b32 s26, s26, 5
	s_add_i32 s26, s26, 16
	v_add_u32_e32 v162, v227, v228
	v_add_u32_e32 v163, v227, v229
	v_add_u32_e32 v164, v227, v230
	v_add_u32_e32 v165, v227, v231
	v_add_u32_e32 v166, v227, v232
	v_add_u32_e32 v167, v227, v233
	v_add_u32_e32 v168, v227, v234
	v_add_u32_e32 v169, v227, v235
	s_nop 0
	s_nop 0
	s_nop 0
	s_add_i32 m0, s26, 0x8000
	s_nop 0
	global_load_lds_dwordx4 v252, s[24:25]
	s_add_i32 m0, s26, 0x8400
	s_nop 0
	global_load_lds_dwordx4 v253, s[24:25]
	s_add_u32 s24, s24, 0x50000
	s_addc_u32 s25, s25, 0

	.amdhsa_kernel _Z14fwd_megakernel6Params
		.amdhsa_group_segment_fixed_size 16
		.amdhsa_private_segment_fixed_size 0
		.amdhsa_kernarg_size 440
		.amdhsa_user_sgpr_count 2
		.amdhsa_user_sgpr_dispatch_ptr 0
		.amdhsa_user_sgpr_queue_ptr 0
		.amdhsa_user_sgpr_kernarg_segment_ptr 1
		.amdhsa_user_sgpr_dispatch_id 0
		.amdhsa_user_sgpr_kernarg_preload_length 0
		.amdhsa_user_sgpr_kernarg_preload_offset 0
		.amdhsa_user_sgpr_private_segment_size 0
		.amdhsa_uses_dynamic_stack 0
		.amdhsa_enable_private_segment 0
		.amdhsa_system_sgpr_workgroup_id_x 1
		.amdhsa_system_sgpr_workgroup_id_y 0
		.amdhsa_system_sgpr_workgroup_id_z 0
		.amdhsa_system_sgpr_workgroup_info 0
		.amdhsa_system_vgpr_workitem_id 2
		.amdhsa_next_free_vgpr 255
		.amdhsa_next_free_sgpr 102
		.amdhsa_accum_offset 256
		.amdhsa_reserve_vcc 1
		.amdhsa_float_round_mode_32 0
		.amdhsa_float_round_mode_16_64 0
		.amdhsa_float_denorm_mode_32 3
		.amdhsa_float_denorm_mode_16_64 3
		.amdhsa_dx10_clamp 1
		.amdhsa_ieee_mode 1
		.amdhsa_fp16_overflow 0
		.amdhsa_tg_split 0
		.amdhsa_exception_fp_ieee_invalid_op 0
		.amdhsa_exception_fp_denorm_src 0
		.amdhsa_exception_fp_ieee_div_zero 0
		.amdhsa_exception_fp_ieee_overflow 0
		.amdhsa_exception_fp_ieee_underflow 0
		.amdhsa_exception_fp_ieee_inexact 0
		.amdhsa_exception_int_div_zero 0
	.end_amdhsa_kernel

amdhsa.kernels:
  - .agpr_count:     0
    .args:
      - .offset:         0
        .size:           184
        .value_kind:     by_value
      - .offset:         184
        .size:           4
        .value_kind:     hidden_block_count_x
      - .offset:         188
        .size:           4
        .value_kind:     hidden_block_count_y
      - .offset:         192
        .size:           4
        .value_kind:     hidden_block_count_z
      - .offset:         196
        .size:           2
        .value_kind:     hidden_group_size_x
      - .offset:         198
        .size:           2
        .value_kind:     hidden_group_size_y
      - .offset:         200
        .size:           2
        .value_kind:     hidden_group_size_z
      - .offset:         202
        .size:           2
        .value_kind:     hidden_remainder_x
      - .offset:         204
        .size:           2
        .value_kind:     hidden_remainder_y
      - .offset:         206
        .size:           2
        .value_kind:     hidden_remainder_z
      - .offset:         224
        .size:           8
        .value_kind:     hidden_global_offset_x
      - .offset:         232
        .size:           8
        .value_kind:     hidden_global_offset_y
      - .offset:         240
        .size:           8
        .value_kind:     hidden_global_offset_z
      - .offset:         248
        .size:           2
        .value_kind:     hidden_grid_dims
      - .offset:         272
        .size:           8
        .value_kind:     hidden_multigrid_sync_arg
      - .offset:         304
        .size:           4
        .value_kind:     hidden_dynamic_lds_size
    .group_segment_fixed_size: 16
    .kernarg_segment_align: 8
    .kernarg_segment_size: 440
    .language:       OpenCL C
    .language_version:
      - 2
      - 0
    .max_flat_workgroup_size: 512
    .name:           _Z14fwd_megakernel6Params
    .private_segment_fixed_size: 0
    .sgpr_count:     108
    .sgpr_spill_count: 56
    .symbol:         _Z14fwd_megakernel6Params.kd
    .uniform_work_group_size: 1
    .uses_dynamic_stack: false
    .vgpr_count:     255
    .vgpr_spill_count: 0
    .wavefront_size: 64
